# attention: static s_setprio 1 given to the lag waves (4-7) instead of the lead waves
# speedup vs baseline: 1.0017x; 1.0017x over previous
.LBB0_489:
	s_lshr_b32 s0, s1, 5
	v_readfirstlane_b32 s6, v0
	s_sub_i32 s59, 7, s0
	s_lshr_b32 s7, s6, 7
	s_xor_b32 s58, s7, 2
	s_or_b32 s7, s59, s56
	s_andn2_b32 s1, 31, s1
	s_bfe_u32 s57, s6, 0x10006
	s_mul_i32 s8, s7, 0x104000
	s_add_u32 s28, s40, s8
	s_addc_u32 s29, s41, 0
	s_add_u32 s30, s38, s8
	s_addc_u32 s31, s39, 0
	s_lshl_b32 s61, s1, 1
	s_lshl_b32 s60, s1, 7
	s_or_b32 s65, s61, 1
	s_lshl_b32 s63, s58, 5
	v_or_b32_e32 v2, s60, v208
	s_lshl_b32 s8, s65, 13
	v_add_u32_e32 v172, s63, v2
	v_add_lshl_u32 v2, s8, v191, 1
	v_lshl_add_u64 v[12:13], s[28:29], 0, v[2:3]
	v_add_co_u32_e32 v12, vcc, s43, v12
	v_lshl_add_u64 v[14:15], s[30:31], 0, v[2:3]
	s_nop 0
	v_addc_co_u32_e32 v13, vcc, 0, v13, vcc
	v_mov_b32_e32 v173, v3
	v_add_co_u32_e32 v16, vcc, s43, v14
	v_lshlrev_b64 v[20:21], 11, v[172:173]
	s_nop 0
	v_addc_co_u32_e32 v17, vcc, 0, v15, vcc
	global_load_dwordx4 v[4:7], v2, s[28:29]
	global_load_dwordx4 v[8:11], v2, s[30:31]
	s_nop 0
	global_load_dwordx4 v[12:15], v[12:13], off
	s_nop 0
	global_load_dwordx4 v[16:19], v[16:17], off
	v_lshl_add_u64 v[20:21], s[12:13], 0, v[20:21]
	s_lshl_b32 s10, s59, 8
	v_lshl_add_u64 v[20:21], v[20:21], 0, s[10:11]
	s_lshl_b32 s10, s57, 7
	v_lshl_add_u64 v[20:21], v[20:21], 0, s[10:11]
	v_lshlrev_b32_e32 v170, 1, v152
	v_mov_b32_e32 v171, v3
	v_lshl_add_u64 v[20:21], v[20:21], 0, v[170:171]
	global_load_dwordx4 v[118:121], v[20:21], off
	global_load_dwordx4 v[122:125], v[20:21], off offset:32
	global_load_dwordx4 v[126:129], v[20:21], off offset:64
	global_load_dwordx4 v[130:133], v[20:21], off offset:96
	s_lshl_b32 s64, s1, 14
	v_or_b32_e32 v2, s64, v191
	v_lshlrev_b32_e32 v2, 1, v2
	v_lshl_add_u64 v[20:21], s[28:29], 0, v[2:3]
	v_add_co_u32_e32 v20, vcc, s43, v20
	v_lshl_add_u64 v[22:23], s[30:31], 0, v[2:3]
	s_nop 0
	v_addc_co_u32_e32 v21, vcc, 0, v21, vcc
	v_add_co_u32_e32 v22, vcc, s43, v22
	global_load_dwordx4 v[134:137], v2, s[28:29]
	global_load_dwordx4 v[138:141], v2, s[30:31]
	v_addc_co_u32_e32 v23, vcc, 0, v23, vcc
	global_load_dwordx4 v[142:145], v[20:21], off
	global_load_dwordx4 v[146:149], v[22:23], off
	s_lshl_b32 s1, s7, 6
	s_lshl_b32 s7, s57, 5
	s_add_i32 s1, s1, 0
	s_add_i32 s1, s1, s7
	s_add_i32 s1, s1, 0x22000
	v_mov_b32_e32 v2, s1
	s_cmpk_gt_u32 s6, 0xff
	s_waitcnt vmcnt(11)
	ds_write_b128 v194, v[4:7]
	s_waitcnt vmcnt(10)
	ds_write_b128 v192, v[8:11] offset:52224
	s_waitcnt vmcnt(9)
	ds_write_b128 v194, v[12:15] offset:8704
	s_waitcnt vmcnt(8)
	ds_write_b128 v192, v[16:19] offset:52288
	s_waitcnt lgkmcnt(0)
	s_barrier
	ds_read_b128 v[20:23], v2
	ds_read_b128 v[4:7], v2 offset:16
	s_waitcnt vmcnt(7)
	v_and_b32_e32 v8, 0xffff0000, v118
	v_lshlrev_b32_e32 v2, 16, v118
	v_mul_f32_e32 v24, v8, v8
	v_lshlrev_b32_e32 v9, 16, v119
	v_fmac_f32_e32 v24, v2, v2
	v_and_b32_e32 v10, 0xffff0000, v119
	v_fmac_f32_e32 v24, v9, v9
	v_lshlrev_b32_e32 v11, 16, v120
	v_fmac_f32_e32 v24, v10, v10
	v_and_b32_e32 v12, 0xffff0000, v120
	v_fmac_f32_e32 v24, v11, v11
	v_lshlrev_b32_e32 v13, 16, v121
	v_fmac_f32_e32 v24, v12, v12
	v_and_b32_e32 v14, 0xffff0000, v121
	v_fmac_f32_e32 v24, v13, v13
	s_waitcnt vmcnt(6)
	v_lshlrev_b32_e32 v15, 16, v122
	v_fmac_f32_e32 v24, v14, v14
	v_and_b32_e32 v16, 0xffff0000, v122
	v_fmac_f32_e32 v24, v15, v15
	v_lshlrev_b32_e32 v17, 16, v123
	v_fmac_f32_e32 v24, v16, v16
	v_and_b32_e32 v18, 0xffff0000, v123
	v_fmac_f32_e32 v24, v17, v17
	v_lshlrev_b32_e32 v19, 16, v124
	v_fmac_f32_e32 v24, v18, v18
	v_and_b32_e32 v25, 0xffff0000, v124
	v_fmac_f32_e32 v24, v19, v19
	v_lshlrev_b32_e32 v26, 16, v125
	v_fmac_f32_e32 v24, v25, v25
	v_and_b32_e32 v27, 0xffff0000, v125
	v_fmac_f32_e32 v24, v26, v26
	s_waitcnt vmcnt(5)
	v_lshlrev_b32_e32 v28, 16, v126
	v_fmac_f32_e32 v24, v27, v27
	v_fmac_f32_e32 v24, v28, v28
	v_and_b32_e32 v2, 0xffff0000, v126
	v_fmac_f32_e32 v24, v2, v2
	v_lshlrev_b32_e32 v2, 16, v127
	v_fmac_f32_e32 v24, v2, v2
	v_and_b32_e32 v2, 0xffff0000, v127
	v_fmac_f32_e32 v24, v2, v2
	v_lshlrev_b32_e32 v2, 16, v128
	v_fmac_f32_e32 v24, v2, v2
	v_and_b32_e32 v2, 0xffff0000, v128
	v_fmac_f32_e32 v24, v2, v2
	v_lshlrev_b32_e32 v2, 16, v129
	v_fmac_f32_e32 v24, v2, v2
	v_and_b32_e32 v2, 0xffff0000, v129
	v_fmac_f32_e32 v24, v2, v2
	s_waitcnt vmcnt(4)
	v_lshlrev_b32_e32 v2, 16, v130
	v_fmac_f32_e32 v24, v2, v2
	v_and_b32_e32 v2, 0xffff0000, v130
	v_fmac_f32_e32 v24, v2, v2
	v_lshlrev_b32_e32 v2, 16, v131
	v_fmac_f32_e32 v24, v2, v2
	v_and_b32_e32 v2, 0xffff0000, v131
	v_fmac_f32_e32 v24, v2, v2
	v_lshlrev_b32_e32 v2, 16, v132
	v_fmac_f32_e32 v24, v2, v2
	v_and_b32_e32 v2, 0xffff0000, v132
	v_fmac_f32_e32 v24, v2, v2
	v_lshlrev_b32_e32 v2, 16, v133
	v_fmac_f32_e32 v24, v2, v2
	v_and_b32_e32 v2, 0xffff0000, v133
	v_fmac_f32_e32 v24, v2, v2
	v_mov_b32_e32 v25, v24
	s_nop 1
	v_permlane32_swap_b32_e32 v24, v25
	s_cbranch_scc0 .LBB0_491
	s_setprio 1
